# MLP-in hidden activation stored with plain (write-back) stores instead of sc1 write-through, since seams no longer flush L2
# speedup vs baseline: 1.0381x; 1.0003x over previous
; __device__ __forceinline__ unsigned cvt_pk_bf16(float lo, float hi) { f32x2 v = {lo, hi}; bf16x2_t b = __builtin_convertvector(v, bf16x2_t); return __builtin_bit_cast(unsigned, b); }
;     __device__ __forceinline__ void operator()(const f32x4 (&acc)[2][2][4][2], const Unit& u, int wr, int wc, int fr, int fq) const {
;     ...
;             for (int m = 0; m < 4; ++m) {
;                 const int row = row0 + ai * HALF + m * 16;
;                 float sc = 1.f; u32x4 bw0, bw1;
;                 if (has_scale) sc = xl[2560 + ai * HALF + wr * 64 + m * 16 + fr];
;                 if (MODE == 3) { bw0 = bnn[m][0]; bw1 = bnn[m][1]; }
;                 if (MODE == 0 || MODE == 1) {
; #pragma unroll
;                     for (int bj = 0; bj < 2; ++bj) {
;                         const int hf = 2 * u.pn + bj;
;                         bf16_t* dst;
;                         if (split2) dst = ((hf & 1) ? O2 : O) + (size_t)row * ldc + (hf >> 1) * 128 + wc * 32 + 8 * fq;
;                         else dst = O + (size_t)row * ldc + hf * 128 + wc * 32 + 8 * fq;
;                         f32x4 v0 = acc[ai][bj][m][0] * sc, v1 = acc[ai][bj][m][1] * sc;
;                         if (MODE == 1) {
; #pragma unroll
;                             for (int e = 0; e < 4; ++e) { float a = fmaxf(v0[e], 0.f), b = fmaxf(v1[e], 0.f); v0[e] = a * a; v1[e] = b * b; }
;                         }
;                         u32x4 w; w.x = cvt_pk_bf16(v0[0], v0[1]); w.y = cvt_pk_bf16(v0[2], v0[3]); w.z = cvt_pk_bf16(v1[0], v1[1]); w.w = cvt_pk_bf16(v1[2], v1[3]);
;                         if (MODE == 1) asm volatile("global_store_dwordx4 %0, %1, off sc1\n\ts_nop 1" :: "v"(dst), "v"(w) : "memory");
;                         else *(u32x4*)dst = w;
;                     }
.LBB0_1070:
	v_lshl_add_u32 v142, s46, 8, v144
	v_max_f32_e32 v120, v120, v120
	v_max_f32_e32 v121, v121, v121
	s_lshl_b32 s6, s44, 8
	v_ashrrev_i32_e32 v143, 31, v142
	v_max_f32_e32 v120, 0, v120
	v_max_f32_e32 v121, 0, v121
	v_lshlrev_b64 v[140:141], 13, v[142:143]
	s_ashr_i32 s7, s6, 31
	v_pk_mul_f32 v[148:149], v[120:121], v[120:121]
	v_max_f32_e32 v121, v122, v122
	v_max_f32_e32 v123, v123, v123
	v_lshl_add_u64 v[140:141], s[88:89], 0, v[140:141]
	s_lshl_b64 s[6:7], s[6:7], 1
	v_max_f32_e32 v124, v124, v124
	v_max_f32_e32 v125, v125, v125
	v_max_f32_e32 v120, v126, v126
	v_max_f32_e32 v122, 0, v121
	v_max_f32_e32 v121, v127, v127
	v_max_f32_e32 v123, 0, v123
	v_lshl_add_u64 v[140:141], v[140:141], 0, s[6:7]
	v_max_f32_e32 v124, 0, v124
	v_max_f32_e32 v125, 0, v125
	v_max_f32_e32 v120, 0, v120
	v_max_f32_e32 v121, 0, v121
	v_pk_mul_f32 v[150:151], v[122:123], v[122:123]
	v_max_f32_e32 v112, v112, v112
	v_max_f32_e32 v113, v113, v113
	v_lshl_add_u64 v[140:141], v[140:141], 0, s[50:51]
	v_pk_mul_f32 v[124:125], v[124:125], v[124:125]
	v_pk_mul_f32 v[126:127], v[120:121], v[120:121]
	v_cvt_pk_bf16_f32 v122, v148, v149
	v_cvt_pk_bf16_f32 v123, v150, v151
	v_max_f32_e32 v112, 0, v112
	v_max_f32_e32 v113, 0, v113
	v_lshl_add_u64 v[140:141], v[140:141], 0, v[180:181]
	v_cvt_pk_bf16_f32 v120, v124, v125
	v_cvt_pk_bf16_f32 v121, v126, v127
	global_store_dwordx4 v[140:141], v[120:123], off
	s_nop 1
	v_max_f32_e32 v116, v116, v116
	v_max_f32_e32 v117, v117, v117
	v_pk_mul_f32 v[122:123], v[112:113], v[112:113]
	v_max_f32_e32 v113, v114, v114
	v_max_f32_e32 v116, 0, v116
	v_max_f32_e32 v117, 0, v117
	v_max_f32_e32 v112, v118, v118
	v_max_f32_e32 v114, 0, v113
	v_max_f32_e32 v113, v119, v119
	v_max_f32_e32 v115, v115, v115
	v_pk_mul_f32 v[116:117], v[116:117], v[116:117]
	v_max_f32_e32 v112, 0, v112
	v_max_f32_e32 v113, 0, v113
	v_max_f32_e32 v115, 0, v115
	s_mov_b64 s[26:27], 0x100
	v_pk_mul_f32 v[118:119], v[112:113], v[112:113]
	v_pk_mul_f32 v[124:125], v[114:115], v[114:115]
	v_cvt_pk_bf16_f32 v112, v116, v117
	v_lshl_add_u64 v[120:121], v[140:141], 0, s[26:27]
	v_cvt_pk_bf16_f32 v113, v118, v119
	v_cvt_pk_bf16_f32 v114, v122, v123
	v_cvt_pk_bf16_f32 v115, v124, v125
	global_store_dwordx4 v[120:121], v[112:115], off
	s_nop 1
	v_or_b32_e32 v112, 16, v142
	v_max_f32_e32 v104, v104, v104
	v_max_f32_e32 v105, v105, v105
	v_ashrrev_i32_e32 v113, 31, v112
	v_max_f32_e32 v104, 0, v104
	v_max_f32_e32 v105, 0, v105
	v_lshlrev_b64 v[112:113], 13, v[112:113]
	v_pk_mul_f32 v[114:115], v[104:105], v[104:105]
	v_max_f32_e32 v105, v106, v106
	v_max_f32_e32 v107, v107, v107
	v_lshl_add_u64 v[112:113], s[88:89], 0, v[112:113]
	v_max_f32_e32 v108, v108, v108
	v_max_f32_e32 v109, v109, v109
	v_max_f32_e32 v104, v110, v110
	v_max_f32_e32 v106, 0, v105
	v_max_f32_e32 v105, v111, v111
	v_max_f32_e32 v107, 0, v107
	v_lshl_add_u64 v[112:113], v[112:113], 0, s[6:7]
	v_max_f32_e32 v108, 0, v108
	v_max_f32_e32 v109, 0, v109
	v_max_f32_e32 v104, 0, v104
	v_max_f32_e32 v105, 0, v105
	v_pk_mul_f32 v[116:117], v[106:107], v[106:107]
	v_max_f32_e32 v96, v96, v96
	v_max_f32_e32 v97, v97, v97
	v_lshl_add_u64 v[112:113], v[112:113], 0, s[50:51]
	v_pk_mul_f32 v[108:109], v[108:109], v[108:109]
	v_pk_mul_f32 v[110:111], v[104:105], v[104:105]
	v_cvt_pk_bf16_f32 v106, v114, v115
	v_cvt_pk_bf16_f32 v107, v116, v117
	v_max_f32_e32 v96, 0, v96
	v_max_f32_e32 v97, 0, v97
	v_lshl_add_u64 v[112:113], v[112:113], 0, v[180:181]
	v_cvt_pk_bf16_f32 v104, v108, v109
	v_cvt_pk_bf16_f32 v105, v110, v111
	global_store_dwordx4 v[112:113], v[104:107], off
	s_nop 1
	v_max_f32_e32 v100, v100, v100
	v_max_f32_e32 v101, v101, v101
	v_pk_mul_f32 v[106:107], v[96:97], v[96:97]
	v_max_f32_e32 v97, v98, v98
	v_max_f32_e32 v100, 0, v100
	v_max_f32_e32 v101, 0, v101
	v_max_f32_e32 v96, v102, v102
	v_max_f32_e32 v98, 0, v97
	v_max_f32_e32 v97, v103, v103
	v_max_f32_e32 v99, v99, v99
	v_pk_mul_f32 v[100:101], v[100:101], v[100:101]
	v_max_f32_e32 v96, 0, v96
	v_max_f32_e32 v97, 0, v97
	v_max_f32_e32 v99, 0, v99
	v_pk_mul_f32 v[102:103], v[96:97], v[96:97]
	v_pk_mul_f32 v[108:109], v[98:99], v[98:99]
	v_cvt_pk_bf16_f32 v96, v100, v101
	v_lshl_add_u64 v[104:105], v[112:113], 0, s[26:27]
	v_cvt_pk_bf16_f32 v97, v102, v103
	v_cvt_pk_bf16_f32 v98, v106, v107
	v_cvt_pk_bf16_f32 v99, v108, v109
	global_store_dwordx4 v[104:105], v[96:99], off
	s_nop 1
	v_or_b32_e32 v96, 32, v142
	v_max_f32_e32 v88, v88, v88
	v_max_f32_e32 v89, v89, v89
	v_ashrrev_i32_e32 v97, 31, v96
	v_max_f32_e32 v88, 0, v88
	v_max_f32_e32 v89, 0, v89
	v_lshlrev_b64 v[96:97], 13, v[96:97]
	v_pk_mul_f32 v[98:99], v[88:89], v[88:89]
	v_max_f32_e32 v89, v90, v90
	v_max_f32_e32 v91, v91, v91
	v_lshl_add_u64 v[96:97], s[88:89], 0, v[96:97]
	v_max_f32_e32 v92, v92, v92
	v_max_f32_e32 v93, v93, v93
	v_max_f32_e32 v88, v94, v94
	v_max_f32_e32 v90, 0, v89
	v_max_f32_e32 v89, v95, v95
	v_max_f32_e32 v91, 0, v91
	v_lshl_add_u64 v[96:97], v[96:97], 0, s[6:7]
	v_max_f32_e32 v92, 0, v92
	v_max_f32_e32 v93, 0, v93
	v_max_f32_e32 v88, 0, v88
	v_max_f32_e32 v89, 0, v89
	v_pk_mul_f32 v[100:101], v[90:91], v[90:91]
	v_max_f32_e32 v80, v80, v80
	v_max_f32_e32 v81, v81, v81
	v_lshl_add_u64 v[96:97], v[96:97], 0, s[50:51]
	v_pk_mul_f32 v[92:93], v[92:93], v[92:93]
	v_pk_mul_f32 v[94:95], v[88:89], v[88:89]
	v_cvt_pk_bf16_f32 v90, v98, v99
	v_cvt_pk_bf16_f32 v91, v100, v101
	v_max_f32_e32 v80, 0, v80
	v_max_f32_e32 v81, 0, v81
	v_lshl_add_u64 v[96:97], v[96:97], 0, v[180:181]
	v_cvt_pk_bf16_f32 v88, v92, v93
	v_cvt_pk_bf16_f32 v89, v94, v95
	global_store_dwordx4 v[96:97], v[88:91], off
	s_nop 1
	v_max_f32_e32 v84, v84, v84
	v_max_f32_e32 v85, v85, v85
; __device__ __forceinline__ unsigned cvt_pk_bf16(float lo, float hi) { f32x2 v = {lo, hi}; bf16x2_t b = __builtin_convertvector(v, bf16x2_t); return __builtin_bit_cast(unsigned, b); }
;     __device__ __forceinline__ void operator()(const f32x4 (&acc)[2][2][4][2], const Unit& u, int wr, int wc, int fr, int fq) const {
;     ...
;             for (int m = 0; m < 4; ++m) {
;                 const int row = row0 + ai * HALF + m * 16;
;                 float sc = 1.f; u32x4 bw0, bw1;
;                 if (has_scale) sc = xl[2560 + ai * HALF + wr * 64 + m * 16 + fr];
;                 if (MODE == 3) { bw0 = bnn[m][0]; bw1 = bnn[m][1]; }
;                 if (MODE == 0 || MODE == 1) {
; #pragma unroll
;                     for (int bj = 0; bj < 2; ++bj) {
;                         const int hf = 2 * u.pn + bj;
;                         bf16_t* dst;
;                         if (split2) dst = ((hf & 1) ? O2 : O) + (size_t)row * ldc + (hf >> 1) * 128 + wc * 32 + 8 * fq;
;                         else dst = O + (size_t)row * ldc + hf * 128 + wc * 32 + 8 * fq;
;                         f32x4 v0 = acc[ai][bj][m][0] * sc, v1 = acc[ai][bj][m][1] * sc;
;                         if (MODE == 1) {
; #pragma unroll
;                             for (int e = 0; e < 4; ++e) { float a = fmaxf(v0[e], 0.f), b = fmaxf(v1[e], 0.f); v0[e] = a * a; v1[e] = b * b; }
;                         }
;                         u32x4 w; w.x = cvt_pk_bf16(v0[0], v0[1]); w.y = cvt_pk_bf16(v0[2], v0[3]); w.z = cvt_pk_bf16(v1[0], v1[1]); w.w = cvt_pk_bf16(v1[2], v1[3]);
;                         if (MODE == 1) asm volatile("global_store_dwordx4 %0, %1, off sc1\n\ts_nop 1" :: "v"(dst), "v"(w) : "memory");
;                         else *(u32x4*)dst = w;
;                     }
	v_pk_mul_f32 v[90:91], v[80:81], v[80:81]
	v_max_f32_e32 v81, v82, v82
	v_max_f32_e32 v84, 0, v84
	v_max_f32_e32 v85, 0, v85
	v_max_f32_e32 v80, v86, v86
	v_max_f32_e32 v82, 0, v81
	v_max_f32_e32 v81, v87, v87
	v_max_f32_e32 v83, v83, v83
	v_pk_mul_f32 v[84:85], v[84:85], v[84:85]
	v_max_f32_e32 v80, 0, v80
	v_max_f32_e32 v81, 0, v81
	v_max_f32_e32 v83, 0, v83
	v_pk_mul_f32 v[86:87], v[80:81], v[80:81]
	v_pk_mul_f32 v[92:93], v[82:83], v[82:83]
	v_cvt_pk_bf16_f32 v80, v84, v85
	v_lshl_add_u64 v[88:89], v[96:97], 0, s[26:27]
	v_cvt_pk_bf16_f32 v81, v86, v87
	v_cvt_pk_bf16_f32 v82, v90, v91
	v_cvt_pk_bf16_f32 v83, v92, v93
	global_store_dwordx4 v[88:89], v[80:83], off
	s_nop 1
	v_or_b32_e32 v80, 48, v142
	v_max_f32_e32 v72, v72, v72
	v_max_f32_e32 v73, v73, v73
	v_ashrrev_i32_e32 v81, 31, v80
	v_max_f32_e32 v72, 0, v72
	v_max_f32_e32 v73, 0, v73
	v_lshlrev_b64 v[80:81], 13, v[80:81]
	v_pk_mul_f32 v[82:83], v[72:73], v[72:73]
	v_max_f32_e32 v73, v74, v74
	v_max_f32_e32 v75, v75, v75
	v_lshl_add_u64 v[80:81], s[88:89], 0, v[80:81]
	v_max_f32_e32 v76, v76, v76
	v_max_f32_e32 v77, v77, v77
	v_max_f32_e32 v72, v78, v78
	v_max_f32_e32 v74, 0, v73
	v_max_f32_e32 v73, v79, v79
	v_max_f32_e32 v75, 0, v75
	v_lshl_add_u64 v[80:81], v[80:81], 0, s[6:7]
	v_max_f32_e32 v76, 0, v76
	v_max_f32_e32 v77, 0, v77
	v_max_f32_e32 v72, 0, v72
	v_max_f32_e32 v73, 0, v73
	v_pk_mul_f32 v[84:85], v[74:75], v[74:75]
	v_max_f32_e32 v64, v64, v64
	v_max_f32_e32 v65, v65, v65
	v_lshl_add_u64 v[80:81], v[80:81], 0, s[50:51]
	v_pk_mul_f32 v[76:77], v[76:77], v[76:77]
	v_pk_mul_f32 v[78:79], v[72:73], v[72:73]
	v_cvt_pk_bf16_f32 v74, v82, v83
	v_cvt_pk_bf16_f32 v75, v84, v85
	v_max_f32_e32 v64, 0, v64
	v_max_f32_e32 v65, 0, v65
	v_lshl_add_u64 v[80:81], v[80:81], 0, v[180:181]
	v_cvt_pk_bf16_f32 v72, v76, v77
	v_cvt_pk_bf16_f32 v73, v78, v79
	global_store_dwordx4 v[80:81], v[72:75], off
	s_nop 1
	v_pk_mul_f32 v[74:75], v[64:65], v[64:65]
	v_max_f32_e32 v65, v66, v66
	v_max_f32_e32 v67, v67, v67
	v_max_f32_e32 v68, v68, v68
	v_max_f32_e32 v69, v69, v69
	v_max_f32_e32 v64, v70, v70
	v_max_f32_e32 v66, 0, v65
	v_max_f32_e32 v65, v71, v71
	v_max_f32_e32 v67, 0, v67
	v_max_f32_e32 v68, 0, v68
	v_max_f32_e32 v69, 0, v69
	v_max_f32_e32 v64, 0, v64
	v_max_f32_e32 v65, 0, v65
	v_pk_mul_f32 v[76:77], v[66:67], v[66:67]
	v_max_f32_e32 v56, v56, v56
	v_max_f32_e32 v57, v57, v57
	v_pk_mul_f32 v[68:69], v[68:69], v[68:69]
	v_pk_mul_f32 v[70:71], v[64:65], v[64:65]
	v_cvt_pk_bf16_f32 v66, v74, v75
	v_cvt_pk_bf16_f32 v67, v76, v77
	v_max_f32_e32 v56, 0, v56
	v_max_f32_e32 v57, 0, v57
	v_lshl_add_u64 v[72:73], v[80:81], 0, s[26:27]
	v_cvt_pk_bf16_f32 v64, v68, v69
	v_cvt_pk_bf16_f32 v65, v70, v71
	global_store_dwordx4 v[72:73], v[64:67], off
	s_nop 1
	v_pk_mul_f32 v[66:67], v[56:57], v[56:57]
	v_max_f32_e32 v57, v58, v58
	v_max_f32_e32 v59, v59, v59
	v_max_f32_e32 v60, v60, v60
	v_max_f32_e32 v61, v61, v61
	v_max_f32_e32 v56, v62, v62
	v_max_f32_e32 v58, 0, v57
	v_max_f32_e32 v57, v63, v63
	v_max_f32_e32 v59, 0, v59
	v_max_f32_e32 v60, 0, v60
	v_max_f32_e32 v61, 0, v61
	v_max_f32_e32 v56, 0, v56
	v_max_f32_e32 v57, 0, v57
	v_pk_mul_f32 v[68:69], v[58:59], v[58:59]
	v_max_f32_e32 v48, v48, v48
	v_max_f32_e32 v49, v49, v49
	s_mov_b64 s[6:7], 0x100000
	v_pk_mul_f32 v[60:61], v[60:61], v[60:61]
	v_pk_mul_f32 v[62:63], v[56:57], v[56:57]
	v_cvt_pk_bf16_f32 v58, v66, v67
	v_cvt_pk_bf16_f32 v59, v68, v69
	v_max_f32_e32 v48, 0, v48
	v_max_f32_e32 v49, 0, v49
	v_lshl_add_u64 v[64:65], v[140:141], 0, s[6:7]
	v_cvt_pk_bf16_f32 v56, v60, v61
	v_cvt_pk_bf16_f32 v57, v62, v63
	global_store_dwordx4 v[64:65], v[56:59], off
	s_nop 1
	v_pk_mul_f32 v[58:59], v[48:49], v[48:49]
	v_max_f32_e32 v49, v50, v50
	v_max_f32_e32 v51, v51, v51
	v_max_f32_e32 v52, v52, v52
	v_max_f32_e32 v53, v53, v53
	v_max_f32_e32 v48, v54, v54
	v_max_f32_e32 v50, 0, v49
	v_max_f32_e32 v49, v55, v55
	v_max_f32_e32 v51, 0, v51
	v_max_f32_e32 v52, 0, v52
	v_max_f32_e32 v53, 0, v53
	v_max_f32_e32 v48, 0, v48
	v_max_f32_e32 v49, 0, v49
	v_pk_mul_f32 v[60:61], v[50:51], v[50:51]
	v_max_f32_e32 v40, v40, v40
	v_max_f32_e32 v41, v41, v41
	s_mov_b64 s[6:7], 0x100100
	v_pk_mul_f32 v[52:53], v[52:53], v[52:53]
	v_pk_mul_f32 v[54:55], v[48:49], v[48:49]
	v_cvt_pk_bf16_f32 v50, v58, v59
	v_cvt_pk_bf16_f32 v51, v60, v61
	v_max_f32_e32 v40, 0, v40
	v_max_f32_e32 v41, 0, v41
	v_lshl_add_u64 v[56:57], v[140:141], 0, s[6:7]
	v_cvt_pk_bf16_f32 v48, v52, v53
	v_cvt_pk_bf16_f32 v49, v54, v55
	global_store_dwordx4 v[56:57], v[48:51], off
	s_nop 1
	v_pk_mul_f32 v[50:51], v[40:41], v[40:41]
	v_max_f32_e32 v41, v42, v42
	v_max_f32_e32 v43, v43, v43
	v_max_f32_e32 v44, v44, v44
	v_max_f32_e32 v45, v45, v45
	v_max_f32_e32 v40, v46, v46
	v_max_f32_e32 v42, 0, v41
	v_max_f32_e32 v41, v47, v47
	v_max_f32_e32 v43, 0, v43
	v_max_f32_e32 v44, 0, v44
	v_max_f32_e32 v45, 0, v45
	v_max_f32_e32 v40, 0, v40
	v_max_f32_e32 v41, 0, v41
;     __device__ __forceinline__ void operator()(const f32x4 (&acc)[2][2][4][2], const Unit& u, int wr, int wc, int fr, int fq) const {
;     ...
;             for (int m = 0; m < 4; ++m) {
;                 const int row = row0 + ai * HALF + m * 16;
;                 float sc = 1.f; u32x4 bw0, bw1;
;                 if (has_scale) sc = xl[2560 + ai * HALF + wr * 64 + m * 16 + fr];
;                 if (MODE == 3) { bw0 = bnn[m][0]; bw1 = bnn[m][1]; }
;                 if (MODE == 0 || MODE == 1) {
; #pragma unroll
;                     for (int bj = 0; bj < 2; ++bj) {
;                         const int hf = 2 * u.pn + bj;
;                         bf16_t* dst;
;                         if (split2) dst = ((hf & 1) ? O2 : O) + (size_t)row * ldc + (hf >> 1) * 128 + wc * 32 + 8 * fq;
;                         else dst = O + (size_t)row * ldc + hf * 128 + wc * 32 + 8 * fq;
;                         f32x4 v0 = acc[ai][bj][m][0] * sc, v1 = acc[ai][bj][m][1] * sc;
;                         if (MODE == 1) {
; #pragma unroll
;                             for (int e = 0; e < 4; ++e) { float a = fmaxf(v0[e], 0.f), b = fmaxf(v1[e], 0.f); v0[e] = a * a; v1[e] = b * b; }
;                         }
;                         u32x4 w; w.x = cvt_pk_bf16(v0[0], v0[1]); w.y = cvt_pk_bf16(v0[2], v0[3]); w.z = cvt_pk_bf16(v1[0], v1[1]); w.w = cvt_pk_bf16(v1[2], v1[3]);
;                         if (MODE == 1) asm volatile("global_store_dwordx4 %0, %1, off sc1\n\ts_nop 1" :: "v"(dst), "v"(w) : "memory");
;                         else *(u32x4*)dst = w;
;                     }
; template <class Epi, class Sched, bool ALIGN_EPI = false, bool SP2 = false>
; __device__ __forceinline__ void gemm_phase(PG8_LAS unsigned char* lds, const Gemm g, const Sched& S, const Epi& E) {
;     ...
;         if constexpr (ALIGN_EPI) { if (wr == 0) PG8_BAR; }
;         if constexpr (!Epi::AFTER_DRAIN) { E(acc, cur, wr, wc, fr, fq); S.done(cur); }
;         if (!has_next) break;
; #pragma unroll
;         for (int a = 0; a < 2; ++a)
; #pragma unroll
;             for (int b = 0; b < 2; ++b)
; #pragma unroll
;                 for (int m = 0; m < 4; ++m)
; #pragma unroll
;                     for (int n = 0; n < 2; ++n) acc[a][b][m][n] = (f32x4){0.f, 0.f, 0.f, 0.f};
;         cur = nxt; cA = nA; cB = nB; ++ui;
;         if constexpr (ALIGN_EPI) { if (wr == 1) PG8_BAR; }
;     }
	v_pk_mul_f32 v[52:53], v[42:43], v[42:43]
	v_max_f32_e32 v32, v32, v32
	v_max_f32_e32 v33, v33, v33
	s_mov_b64 s[6:7], 0x120000
	v_pk_mul_f32 v[44:45], v[44:45], v[44:45]
	v_pk_mul_f32 v[46:47], v[40:41], v[40:41]
	v_cvt_pk_bf16_f32 v42, v50, v51
	v_cvt_pk_bf16_f32 v43, v52, v53
	v_max_f32_e32 v32, 0, v32
	v_max_f32_e32 v33, 0, v33
	v_lshl_add_u64 v[48:49], v[140:141], 0, s[6:7]
	v_cvt_pk_bf16_f32 v40, v44, v45
	v_cvt_pk_bf16_f32 v41, v46, v47
	global_store_dwordx4 v[48:49], v[40:43], off
	s_nop 1
	v_pk_mul_f32 v[42:43], v[32:33], v[32:33]
	v_max_f32_e32 v33, v34, v34
	v_max_f32_e32 v35, v35, v35
	v_max_f32_e32 v36, v36, v36
	v_max_f32_e32 v37, v37, v37
	v_max_f32_e32 v32, v38, v38
	v_max_f32_e32 v34, 0, v33
	v_max_f32_e32 v33, v39, v39
	v_max_f32_e32 v35, 0, v35
	v_max_f32_e32 v36, 0, v36
	v_max_f32_e32 v37, 0, v37
	v_max_f32_e32 v32, 0, v32
	v_max_f32_e32 v33, 0, v33
	v_pk_mul_f32 v[44:45], v[34:35], v[34:35]
	v_max_f32_e32 v24, v24, v24
	v_max_f32_e32 v25, v25, v25
	s_mov_b64 s[6:7], 0x120100
	v_pk_mul_f32 v[36:37], v[36:37], v[36:37]
	v_pk_mul_f32 v[38:39], v[32:33], v[32:33]
	v_cvt_pk_bf16_f32 v34, v42, v43
	v_cvt_pk_bf16_f32 v35, v44, v45
	v_max_f32_e32 v24, 0, v24
	v_max_f32_e32 v25, 0, v25
	v_lshl_add_u64 v[40:41], v[140:141], 0, s[6:7]
	v_cvt_pk_bf16_f32 v32, v36, v37
	v_cvt_pk_bf16_f32 v33, v38, v39
	global_store_dwordx4 v[40:41], v[32:35], off
	s_nop 1
	v_pk_mul_f32 v[34:35], v[24:25], v[24:25]
	v_max_f32_e32 v25, v26, v26
	v_max_f32_e32 v27, v27, v27
	v_max_f32_e32 v28, v28, v28
	v_max_f32_e32 v29, v29, v29
	v_max_f32_e32 v24, v30, v30
	v_max_f32_e32 v26, 0, v25
	v_max_f32_e32 v25, v31, v31
	v_max_f32_e32 v27, 0, v27
	v_max_f32_e32 v28, 0, v28
	v_max_f32_e32 v29, 0, v29
	v_max_f32_e32 v24, 0, v24
	v_max_f32_e32 v25, 0, v25
	v_pk_mul_f32 v[36:37], v[26:27], v[26:27]
	v_max_f32_e32 v16, v16, v16
	v_max_f32_e32 v17, v17, v17
	s_mov_b64 s[6:7], 0x140000
	v_pk_mul_f32 v[28:29], v[28:29], v[28:29]
	v_pk_mul_f32 v[30:31], v[24:25], v[24:25]
	v_cvt_pk_bf16_f32 v26, v34, v35
	v_cvt_pk_bf16_f32 v27, v36, v37
	v_max_f32_e32 v16, 0, v16
	v_max_f32_e32 v17, 0, v17
	v_lshl_add_u64 v[32:33], v[140:141], 0, s[6:7]
	v_cvt_pk_bf16_f32 v24, v28, v29
	v_cvt_pk_bf16_f32 v25, v30, v31
	global_store_dwordx4 v[32:33], v[24:27], off
	s_nop 1
	v_pk_mul_f32 v[26:27], v[16:17], v[16:17]
	v_max_f32_e32 v17, v18, v18
	v_max_f32_e32 v19, v19, v19
	v_max_f32_e32 v20, v20, v20
	v_max_f32_e32 v21, v21, v21
	v_max_f32_e32 v16, v22, v22
	v_max_f32_e32 v18, 0, v17
	v_max_f32_e32 v17, v23, v23
	v_max_f32_e32 v19, 0, v19
	v_max_f32_e32 v20, 0, v20
	v_max_f32_e32 v21, 0, v21
	v_max_f32_e32 v16, 0, v16
	v_max_f32_e32 v17, 0, v17
	v_pk_mul_f32 v[28:29], v[18:19], v[18:19]
	v_max_f32_e32 v8, v8, v8
	v_max_f32_e32 v9, v9, v9
	s_mov_b64 s[6:7], 0x140100
	v_pk_mul_f32 v[20:21], v[20:21], v[20:21]
	v_pk_mul_f32 v[22:23], v[16:17], v[16:17]
	v_cvt_pk_bf16_f32 v18, v26, v27
	v_cvt_pk_bf16_f32 v19, v28, v29
	v_max_f32_e32 v8, 0, v8
	v_max_f32_e32 v9, 0, v9
	v_lshl_add_u64 v[24:25], v[140:141], 0, s[6:7]
	v_cvt_pk_bf16_f32 v16, v20, v21
	v_cvt_pk_bf16_f32 v17, v22, v23
	global_store_dwordx4 v[24:25], v[16:19], off
	s_nop 1
	v_pk_mul_f32 v[18:19], v[8:9], v[8:9]
	v_max_f32_e32 v9, v10, v10
	v_max_f32_e32 v11, v11, v11
	v_max_f32_e32 v12, v12, v12
	v_max_f32_e32 v13, v13, v13
	v_max_f32_e32 v8, v14, v14
	v_max_f32_e32 v10, 0, v9
	v_max_f32_e32 v9, v15, v15
	v_max_f32_e32 v11, 0, v11
	v_max_f32_e32 v12, 0, v12
	v_max_f32_e32 v13, 0, v13
	v_max_f32_e32 v8, 0, v8
	v_max_f32_e32 v9, 0, v9
	v_pk_mul_f32 v[20:21], v[10:11], v[10:11]
	v_max_f32_e32 v0, v0, v0
	v_max_f32_e32 v1, v1, v1
	s_mov_b64 s[6:7], 0x160000
	v_pk_mul_f32 v[12:13], v[12:13], v[12:13]
	v_pk_mul_f32 v[14:15], v[8:9], v[8:9]
	v_cvt_pk_bf16_f32 v10, v18, v19
	v_cvt_pk_bf16_f32 v11, v20, v21
	v_max_f32_e32 v0, 0, v0
	v_max_f32_e32 v1, 0, v1
	v_lshl_add_u64 v[16:17], v[140:141], 0, s[6:7]
	v_cvt_pk_bf16_f32 v8, v12, v13
	v_cvt_pk_bf16_f32 v9, v14, v15
	global_store_dwordx4 v[16:17], v[8:11], off
	s_nop 1
	v_pk_mul_f32 v[10:11], v[0:1], v[0:1]
	v_max_f32_e32 v1, v2, v2
	v_max_f32_e32 v4, v4, v4
	v_max_f32_e32 v5, v5, v5
	v_max_f32_e32 v0, v6, v6
	v_max_f32_e32 v2, 0, v1
	v_max_f32_e32 v1, v7, v7
	v_max_f32_e32 v3, v3, v3
	v_max_f32_e32 v4, 0, v4
	v_max_f32_e32 v5, 0, v5
	v_max_f32_e32 v0, 0, v0
	v_max_f32_e32 v1, 0, v1
	v_max_f32_e32 v3, 0, v3
	s_mov_b64 s[6:7], 0x160100
	v_pk_mul_f32 v[4:5], v[4:5], v[4:5]
	v_pk_mul_f32 v[6:7], v[0:1], v[0:1]
	v_pk_mul_f32 v[12:13], v[2:3], v[2:3]
	v_lshl_add_u64 v[8:9], v[140:141], 0, s[6:7]
	v_cvt_pk_bf16_f32 v0, v4, v5
	v_cvt_pk_bf16_f32 v1, v6, v7
	v_cvt_pk_bf16_f32 v2, v10, v11
	v_cvt_pk_bf16_f32 v3, v12, v13
	global_store_dwordx4 v[8:9], v[0:3], off
	s_nop 1
	s_andn2_b64 vcc, exec, s[38:39]
	s_mov_b64 s[6:7], -1
	s_cbranch_vccnz .LBB0_1058
	s_andn2_b64 vcc, exec, s[0:1]
	s_cbranch_vccnz .LBB0_1057
	s_barrier
	s_branch .LBB0_1057
